# v25 + attention K/V tile DMA: 64-bit VALU address adds replaced by SALU base + 32-bit lane offset (saddr form)
# speedup vs baseline: 1.0046x; 1.0046x over previous
.LBB0_917:
	s_cmp_lt_u32 s94, 3
	s_cselect_b64 s[78:79], -1, 0
	s_and_b64 vcc, exec, s[78:79]
	s_cbranch_vccnz .LBB0_920
	s_add_i32 s3, s33, 0x4000
	s_add_i32 s4, s2, 64
	s_and_b32 s3, s3, 0xc000
	s_lshl_b64 s[12:13], s[4:5], 8
	s_add_i32 s4, s1, s3
	v_subrev_u32_e32 v246, s74, v148
	v_subrev_u32_e32 v247, s76, v150
	s_add_u32 s98, s74, s12
	s_addc_u32 s99, s75, s13
	s_mov_b32 m0, s4
	s_add_i32 s3, s8, s3
	global_load_lds_dwordx4 v246, s[98:99]
	s_add_i32 m0, s4, 0x2000
	s_add_u32 s98, s98, 0x2000
	s_addc_u32 s99, s99, 0
	global_load_lds_dwordx4 v246, s[98:99]
	s_mov_b32 m0, s3
	s_add_u32 s100, s76, s12
	s_addc_u32 s101, s77, s13
	global_load_lds_dwordx4 v247, s[100:101]
	s_add_i32 m0, s3, 0x2000
	s_add_u32 s100, s100, 0x2000
	s_addc_u32 s101, s101, 0
	s_mov_b32 s3, s5
	s_lshl_b64 s[12:13], s[2:3], 8
	s_and_b32 s3, s33, 0xc000
	s_add_i32 s4, s1, s3
	global_load_lds_dwordx4 v247, s[100:101]
	s_add_u32 s98, s74, s12
	s_addc_u32 s99, s75, s13
	s_mov_b32 m0, s4
	s_add_i32 s3, s8, s3
	global_load_lds_dwordx4 v246, s[98:99]
	s_add_i32 m0, s4, 0x2000
	s_add_u32 s98, s98, 0x2000
	s_addc_u32 s99, s99, 0
	global_load_lds_dwordx4 v246, s[98:99]
	s_mov_b32 m0, s3
	s_add_u32 s100, s76, s12
	s_addc_u32 s101, s77, s13
	global_load_lds_dwordx4 v247, s[100:101]
	s_add_i32 m0, s3, 0x2000
	s_add_u32 s100, s100, 0x2000
	s_addc_u32 s101, s101, 0
	global_load_lds_dwordx4 v247, s[100:101]
	s_add_i32 s3, s2, 0xc0
	s_cmp_gt_i32 s3, s90
	s_cbranch_scc0 .LBB0_921

.LBB0_943:
	s_cmp_lt_u32 s92, 3
	s_cselect_b64 s[6:7], -1, 0
	s_and_b64 vcc, exec, s[6:7]
	s_cbranch_vccnz .LBB0_946
	s_add_i32 s3, s0, 0x4000
	s_add_i32 s4, s2, 64
	s_and_b32 s3, s3, 0xc000
	s_lshl_b64 s[12:13], s[4:5], 8
	s_add_i32 s4, s1, s3
	v_subrev_u32_e32 v246, s74, v150
	v_subrev_u32_e32 v247, s76, v152
	s_add_u32 s98, s74, s12
	s_addc_u32 s99, s75, s13
	s_mov_b32 m0, s4
	s_add_i32 s3, s8, s3
	global_load_lds_dwordx4 v246, s[98:99]
	s_add_i32 m0, s4, 0x2000
	s_add_u32 s98, s98, 0x2000
	s_addc_u32 s99, s99, 0
	global_load_lds_dwordx4 v246, s[98:99]
	s_mov_b32 m0, s3
	s_add_u32 s100, s76, s12
	s_addc_u32 s101, s77, s13
	global_load_lds_dwordx4 v247, s[100:101]
	s_add_i32 m0, s3, 0x2000
	s_add_u32 s100, s100, 0x2000
	s_addc_u32 s101, s101, 0
	s_mov_b32 s3, s5
	s_lshl_b64 s[12:13], s[2:3], 8
	s_and_b32 s3, s0, 0xc000
	s_add_i32 s4, s1, s3
	global_load_lds_dwordx4 v247, s[100:101]
	s_add_u32 s98, s74, s12
	s_addc_u32 s99, s75, s13
	s_mov_b32 m0, s4
	s_add_i32 s3, s8, s3
	global_load_lds_dwordx4 v246, s[98:99]
	s_add_i32 m0, s4, 0x2000
	s_add_u32 s98, s98, 0x2000
	s_addc_u32 s99, s99, 0
	global_load_lds_dwordx4 v246, s[98:99]
	s_mov_b32 m0, s3
	s_add_u32 s100, s76, s12
	s_addc_u32 s101, s77, s13
	global_load_lds_dwordx4 v247, s[100:101]
	s_add_i32 m0, s3, 0x2000
	s_add_u32 s100, s100, 0x2000
	s_addc_u32 s101, s101, 0
	global_load_lds_dwordx4 v247, s[100:101]
	s_add_i32 s3, s2, 0xc0
	s_cmp_gt_i32 s3, s80
	s_cbranch_scc0 .LBB0_947

	.amdhsa_kernel _Z8mega_fwd4Args
		.amdhsa_group_segment_fixed_size 0
		.amdhsa_private_segment_fixed_size 0
		.amdhsa_kernarg_size 552
		.amdhsa_user_sgpr_count 2
		.amdhsa_user_sgpr_dispatch_ptr 0
		.amdhsa_user_sgpr_queue_ptr 0
		.amdhsa_user_sgpr_kernarg_segment_ptr 1
		.amdhsa_user_sgpr_dispatch_id 0
		.amdhsa_user_sgpr_kernarg_preload_length 0
		.amdhsa_user_sgpr_kernarg_preload_offset 0
		.amdhsa_user_sgpr_private_segment_size 0
		.amdhsa_uses_dynamic_stack 0
		.amdhsa_enable_private_segment 0
		.amdhsa_system_sgpr_workgroup_id_x 1
		.amdhsa_system_sgpr_workgroup_id_y 0
		.amdhsa_system_sgpr_workgroup_id_z 0
		.amdhsa_system_sgpr_workgroup_info 0
		.amdhsa_system_vgpr_workitem_id 0
		.amdhsa_next_free_vgpr 248
		.amdhsa_next_free_sgpr 102
		.amdhsa_accum_offset 248
		.amdhsa_reserve_vcc 1
		.amdhsa_float_round_mode_32 0
		.amdhsa_float_round_mode_16_64 0
		.amdhsa_float_denorm_mode_32 3
		.amdhsa_float_denorm_mode_16_64 3
		.amdhsa_dx10_clamp 1
		.amdhsa_ieee_mode 1
		.amdhsa_fp16_overflow 0
		.amdhsa_tg_split 0
		.amdhsa_exception_fp_ieee_invalid_op 0
		.amdhsa_exception_fp_denorm_src 0
		.amdhsa_exception_fp_ieee_div_zero 0
		.amdhsa_exception_fp_ieee_overflow 0
		.amdhsa_exception_fp_ieee_underflow 0
		.amdhsa_exception_fp_ieee_inexact 0
		.amdhsa_exception_int_div_zero 0
	.end_amdhsa_kernel

amdhsa.kernels:
  - .agpr_count:     0
    .args:
      - .offset:         0
        .size:           296
        .value_kind:     by_value
      - .offset:         296
        .size:           4
        .value_kind:     hidden_block_count_x
      - .offset:         300
        .size:           4
        .value_kind:     hidden_block_count_y
      - .offset:         304
        .size:           4
        .value_kind:     hidden_block_count_z
      - .offset:         308
        .size:           2
        .value_kind:     hidden_group_size_x
      - .offset:         310
        .size:           2
        .value_kind:     hidden_group_size_y
      - .offset:         312
        .size:           2
        .value_kind:     hidden_group_size_z
      - .offset:         314
        .size:           2
        .value_kind:     hidden_remainder_x
      - .offset:         316
        .size:           2
        .value_kind:     hidden_remainder_y
      - .offset:         318
        .size:           2
        .value_kind:     hidden_remainder_z
      - .offset:         336
        .size:           8
        .value_kind:     hidden_global_offset_x
      - .offset:         344
        .size:           8
        .value_kind:     hidden_global_offset_y
      - .offset:         352
        .size:           8
        .value_kind:     hidden_global_offset_z
      - .offset:         360
        .size:           2
        .value_kind:     hidden_grid_dims
      - .offset:         416
        .size:           4
        .value_kind:     hidden_dynamic_lds_size
    .group_segment_fixed_size: 0
    .kernarg_segment_align: 8
    .kernarg_segment_size: 552
    .language:       OpenCL C
    .language_version:
      - 2
      - 0
    .max_flat_workgroup_size: 512
    .name:           _Z8mega_fwd4Args
    .private_segment_fixed_size: 0
    .sgpr_count:     108
    .sgpr_spill_count: 76
    .symbol:         _Z8mega_fwd4Args.kd
    .uniform_work_group_size: 1
    .uses_dynamic_stack: false
    .vgpr_count:     248
    .vgpr_spill_count: 0
    .wavefront_size: 64
